# plus work-queue fast-fail: a failing pop snapshots the 8 per-XCD queue counters and publishes the exhausted-queue mask in the LDS slot word, so the remaining exhausted queues are skipped without their
# speedup vs baseline: 1.0149x; 1.0041x over previous
.LBB0_1094:
	s_add_u32 s64, s24, 0x404000
	s_addc_u32 s65, s25, 0
	s_lshl_b32 s3, s93, 9
	s_add_i32 s3, s3, 0
	s_add_i32 s3, s3, 0x1b000
	s_add_u32 s62, s24, 0x11c98000
	s_addc_u32 s63, s25, 0
	s_add_i32 s7, 0, 0x21200
	s_getreg_b32 s6, hwreg(HW_REG_XCC_ID, 0, 4)
	s_mov_b32 s13, 0
	v_mov_b32_e32 v1, 0
	v_mov_b32_e32 v136, s7
	s_movk_i32 s29, 0x7f
	s_movk_i32 s30, 0x1a00
	s_movk_i32 s34, 0xc0
	s_movk_i32 s35, 0x90
	s_movk_i32 s46, 0x80
	v_mov_b32_e32 v137, 0xf149f2ca
	v_mov_b32_e32 v138, 0x7f
	s_mov_b32 s99, 0
	s_mov_b32 s56, 0
	s_branch .LBB0_1096

.LBB0_1096:
	s_add_i32 s8, s56, s6
	s_and_b32 s57, s8, 7
	s_bitcmp1_b32 s99, s57
	s_cbranch_scc1 .LBB0_1095
	s_lshl_b32 s8, s57, 2
	s_add_u32 s14, s24, s8
	s_addc_u32 s15, s25, 0
	s_branch .LBB0_1100

.LBB0_1104:
	s_or_b64 exec, exec, s[16:17]
	s_waitcnt vmcnt(0)
	v_readfirstlane_b32 s12, v2
	s_nop 1
	s_cmp_lt_u32 s12, 0x80
	v_mov_b32_e32 v240, 0
	s_cbranch_scc1 .Lqm_ok_mixa
	global_load_dwordx4 v[232:235], v1, s[24:25] offset:64 sc1
	global_load_dwordx4 v[236:239], v1, s[24:25] offset:80 sc1
	s_waitcnt vmcnt(0)
	v_lshrrev_b32_e32 v241, 7, v232
	v_min_u32_e32 v241, 1, v241
	v_lshl_or_b32 v240, v241, 16, v240
	v_lshrrev_b32_e32 v241, 7, v233
	v_min_u32_e32 v241, 1, v241
	v_lshl_or_b32 v240, v241, 17, v240
	v_lshrrev_b32_e32 v241, 7, v234
	v_min_u32_e32 v241, 1, v241
	v_lshl_or_b32 v240, v241, 18, v240
	v_lshrrev_b32_e32 v241, 7, v235
	v_min_u32_e32 v241, 1, v241
	v_lshl_or_b32 v240, v241, 19, v240
	v_lshrrev_b32_e32 v241, 7, v236
	v_min_u32_e32 v241, 1, v241
	v_lshl_or_b32 v240, v241, 20, v240
	v_lshrrev_b32_e32 v241, 7, v237
	v_min_u32_e32 v241, 1, v241
	v_lshl_or_b32 v240, v241, 21, v240
	v_lshrrev_b32_e32 v241, 7, v238
	v_min_u32_e32 v241, 1, v241
	v_lshl_or_b32 v240, v241, 22, v240
	v_lshrrev_b32_e32 v241, 7, v239
	v_min_u32_e32 v241, 1, v241
	v_lshl_or_b32 v240, v241, 23, v240
.Lqm_ok_mixa:
	v_mov_b32_e32 v2, s7
	s_nop 0
	v_add_u32_e32 v0, s12, v0
	v_or_b32_e32 v0, v0, v240
	ds_write_b32 v2, v0

.LBB0_1106:
	s_waitcnt lgkmcnt(0)
	s_barrier
	ds_read_b32 v0, v136
	s_mov_b64 s[8:9], -1
	s_waitcnt lgkmcnt(0)
	s_nop 0
	v_readfirstlane_b32 s98, v0
	v_and_b32_e32 v0, 0xffff, v0
	s_nop 1
	s_lshr_b32 s98, s98, 16
	s_or_b32 s99, s99, s98
	v_cmp_lt_i32_e32 vcc, s29, v0
	v_readfirstlane_b32 s12, v0
	s_cbranch_vccnz .LBB0_1099
	s_lshl_b32 s8, s12, 3
	s_and_b32 s8, s8, 8
	s_or_b32 s8, s8, s57
	s_lshl_b32 s8, s8, 6
	s_ashr_i32 s12, s12, 1
	s_add_i32 s16, s8, s12
	s_bfe_u32 s9, s16, 0x10006
	s_lshl_b32 s8, s9, 3
	s_add_i32 s8, s8, s93
	v_mbcnt_lo_u32_b32 v4, -1, 0
	v_mbcnt_hi_u32_b32 v4, -1, v4
	s_lshl_b32 s12, s12, 5
	v_lshl_add_u32 v2, s8, 7, v4
	v_ashrrev_i32_e32 v3, 31, v2
	v_lshl_add_u64 v[2:3], v[2:3], 2, s[64:65]
	global_load_dword v0, v[2:3], off
	global_load_dword v5, v[2:3], off offset:256
	s_and_b32 s68, s12, 0x7e0
	s_bfe_u32 s12, s12, 0x50006
	v_sub_u32_e64 v7, s68, v138 clamp
	s_lshl_b32 s17, -2, s12
	v_readfirstlane_b32 s18, v7
	s_not_b32 s19, s17
	s_ashr_i32 s17, s16, 7
	s_lshr_b32 s16, s18, 6
	s_lshl_b32 s66, s8, 6
	v_and_b32_e32 v2, 31, v4
	s_cmp_lg_u32 s12, 31
	v_or_b32_e32 v101, s68, v2
	s_cselect_b32 s12, s19, -1
	s_lshl_b32 s16, -1, s16
	v_ashrrev_i32_e32 v3, 5, v4
	v_lshl_or_b32 v98, s17, 11, v101
	s_and_b32 s16, s16, s12
	v_lshl_add_u32 v6, v4, 2, s3
	v_ashrrev_i32_e32 v99, 31, v98
	s_cmp_eq_u32 s16, 0
	v_lshlrev_b32_e32 v100, 2, v3
	s_waitcnt vmcnt(0)
	ds_write2st64_b32 v6, v0, v5 offset1:1
	s_cbranch_scc1 .LBB0_1097
	s_lshl_b32 s12, s66, 1
	s_mul_hi_i32 s18, s17, 0xd00000
	s_mul_i32 s17, s17, 0xd00000
	s_add_u32 s17, s50, s17
	s_addc_u32 s19, s51, s18
	s_lshl_b32 s9, s9, 7
	s_add_u32 s18, s17, s9
	s_addc_u32 s19, s19, 0
	s_lshl_b32 s8, s8, 2
	v_mov_b32_e32 v0, s8
	global_load_dword v21, v0, s[10:11]
	v_add_u32_e32 v0, s91, v4
	s_ff1_i32_b32 s8, s16
	s_add_i32 s9, s16, -1
	v_ashrrev_i32_e32 v22, 3, v0
	v_lshlrev_b32_e32 v0, 4, v4
	s_and_b32 s9, s9, s16
	s_mul_i32 s16, s8, 0x68000
	v_and_b32_e32 v139, 0x70, v0
	v_mul_lo_u32 v0, v22, s30
	s_add_u32 s16, s18, s16
	v_or_b32_e32 v0, v0, v139
	s_addc_u32 s17, s19, 0
	v_mov_b64_e32 v[8:9], s[50:51]
	global_load_dwordx4 v[12:15], v0, s[16:17] offset:2048
	global_load_dwordx4 v[16:19], v0, s[16:17] offset:2304
	v_lshlrev_b32_e32 v10, 3, v3
	v_mad_i64_i32 v[8:9], s[16:17], v98, s30, v[8:9]
	v_ashrrev_i32_e32 v11, 31, v10
	v_lshl_add_u64 v[8:9], v[8:9], 0, s[12:13]
	v_lshl_add_u64 v[8:9], v[10:11], 1, v[8:9]
	global_load_dwordx4 v[66:69], v[8:9], off
	global_load_dwordx4 v[70:73], v[8:9], off offset:32
	global_load_dwordx4 v[74:77], v[8:9], off offset:64
	global_load_dwordx4 v[78:81], v[8:9], off offset:96
	v_lshrrev_b32_e32 v20, 2, v4
	v_mul_lo_u32 v163, v22, s35
	v_lshlrev_b32_e32 v23, 1, v4
	v_and_or_b32 v11, v20, 3, v100
	v_add3_u32 v20, 0, v163, v139
	v_lshlrev_b32_e32 v24, 3, v4
	v_lshlrev_b32_e32 v25, 7, v3
	v_lshlrev_b32_e32 v26, 2, v2
	v_and_b32_e32 v159, 32, v23
	v_mul_lo_u32 v164, v22, s34
	v_mul_u32_u24_e32 v140, 0x90, v2
	v_lshlrev_b32_e32 v141, 4, v3
	v_mov_b32_e32 v2, v1
	v_mov_b32_e32 v3, v1
	v_mov_b32_e32 v4, v1
	v_mov_b32_e32 v5, v1
	v_mov_b32_e32 v6, v1
	v_mov_b32_e32 v7, v1
	v_mov_b32_e32 v8, v1
	v_mov_b32_e32 v9, v1
	v_mov_b32_e32 v10, v1
	v_and_b32_e32 v160, 24, v24
	v_bitop3_b32 v161, v25, s46, v26 bitop3:0x36
	v_mul_lo_u32 v162, v11, s34
	v_mov_b32_e32 v11, v1
	v_mov_b32_e32 v24, v1
	v_mov_b32_e32 v25, v1
	v_mov_b32_e32 v26, v1
	v_mov_b32_e32 v27, v1
	v_mov_b32_e32 v28, v1
	v_mov_b32_e32 v29, v1
	v_mov_b32_e32 v30, v1
	v_mov_b32_e32 v31, v1
	v_lshl_add_u64 v[102:103], s[18:19], 0, v[0:1]
	v_mov_b32_e32 v0, v1
	v_mov_b32_e32 v104, 0
	s_mov_b32 s67, 0
	v_sub_u32_e32 v142, 0, v100
	v_subrev_u32_e32 v143, 32, v101
	v_not_b32_e32 v144, v100
	v_xor_b32_e32 v145, -2, v100
	v_xor_b32_e32 v146, -3, v100
	v_sub_u32_e32 v147, -8, v100
	v_sub_u32_e32 v148, -9, v100
	v_sub_u32_e32 v149, -10, v100
	v_sub_u32_e32 v150, -11, v100
	v_sub_u32_e32 v151, -16, v100
	v_sub_u32_e32 v152, 0xffffffef, v100
	v_sub_u32_e32 v153, 0xffffffee, v100
	v_sub_u32_e32 v154, 0xffffffed, v100
	v_sub_u32_e32 v155, 0xffffffe8, v100
	v_sub_u32_e32 v156, 0xffffffe7, v100
	v_sub_u32_e32 v157, 0xffffffe6, v100
	v_sub_u32_e32 v158, 0xffffffe5, v100
	s_addk_i32 s68, 0xff51
	v_mov_b32_e32 v165, 1.0
	v_mov_b32_e32 v105, v104
	v_mov_b32_e32 v106, v104
	s_waitcnt vmcnt(6)
	v_mad_u64_u32 v[22:23], s[16:17], v22, 48, v[20:21]
	v_mul_f32_e32 v166, 0x3fb8aa3b, v21
	s_waitcnt vmcnt(5)
	ds_write_b128 v20, v[12:15]
	s_waitcnt vmcnt(4)
	ds_write_b128 v22, v[16:19] offset:9216
	v_mov_b32_e32 v12, v1
	v_mov_b32_e32 v13, v1
	v_mov_b32_e32 v14, v1
	v_mov_b32_e32 v15, v1
	v_mov_b32_e32 v16, v1
	v_mov_b32_e32 v17, v1
	v_mov_b32_e32 v18, v1
	v_mov_b32_e32 v19, v1
	v_mov_b32_e32 v20, v1
	v_mov_b32_e32 v21, v1
	v_mov_b32_e32 v22, v1
	v_mov_b32_e32 v23, v1
	v_mov_b64_e32 v[32:33], v[30:31]
	v_mov_b64_e32 v[30:31], v[28:29]
	v_mov_b64_e32 v[28:29], v[26:27]
	v_mov_b64_e32 v[26:27], v[24:25]
	v_mov_b64_e32 v[24:25], v[22:23]
	v_mov_b64_e32 v[22:23], v[20:21]
	v_mov_b64_e32 v[20:21], v[18:19]
	v_mov_b64_e32 v[18:19], v[16:17]
	v_mov_b64_e32 v[16:17], v[14:15]
	v_mov_b64_e32 v[14:15], v[12:13]
	v_mov_b64_e32 v[12:13], v[10:11]
	v_mov_b64_e32 v[10:11], v[8:9]
	v_mov_b64_e32 v[8:9], v[6:7]
	v_mov_b64_e32 v[6:7], v[4:5]
	v_mov_b64_e32 v[4:5], v[2:3]
	v_mov_b64_e32 v[2:3], v[0:1]
	v_mov_b32_e32 v107, v104
	v_mov_b32_e32 v108, v104
	v_mov_b32_e32 v109, v104
	v_mov_b32_e32 v110, v104
	v_mov_b32_e32 v111, v104
	v_mov_b32_e32 v112, v104
	v_mov_b32_e32 v113, v104
	v_mov_b32_e32 v114, v104
	v_mov_b32_e32 v115, v104
	v_mov_b32_e32 v116, v104
	v_mov_b32_e32 v117, v104
	v_mov_b32_e32 v118, v104
	v_mov_b32_e32 v119, v104
	v_mov_b32_e32 v120, v104
	v_mov_b32_e32 v121, v104
	v_mov_b32_e32 v122, v104
	v_mov_b32_e32 v123, v104
	v_mov_b32_e32 v124, v104
	v_mov_b32_e32 v125, v104
	v_mov_b32_e32 v126, v104
	v_mov_b32_e32 v127, v104
	v_mov_b32_e32 v128, v104
	v_mov_b32_e32 v129, v104
	v_mov_b32_e32 v130, v104
	v_mov_b32_e32 v131, v104
	v_mov_b32_e32 v132, v104
	v_mov_b32_e32 v133, v104
	v_mov_b32_e32 v134, v104
	v_mov_b32_e32 v135, v104
	s_mov_b32 s69, s8
	s_waitcnt lgkmcnt(0)
	s_barrier

.LBB0_1237:
	s_lshl_b32 s6, s93, 8
	s_add_i32 s35, s6, 0
	s_add_i32 s81, 0, 0x21200
	s_getreg_b32 s29, hwreg(HW_REG_XCC_ID, 0, 4)
	s_add_i32 s30, s91, 0xfffffe00
	s_mov_b32 s67, 0
	s_add_i32 s35, s35, 0x1c000
	v_mov_b32_e32 v1, 0
	v_mov_b32_e32 v190, s81
	s_movk_i32 s82, 0x7f
	s_movk_i32 s83, 0x200
	s_movk_i32 s84, 0x1a00
	s_movk_i32 s85, 0xc0
	s_movk_i32 s86, 0x90
	v_mov_b32_e32 v191, 0xf149f2ca
	s_mov_b32 s87, 0x4d800000
	s_add_i32 s88, 0, 0x20100
	s_add_i32 s89, 0, 0x20104
	v_mov_b32_e32 v192, 0x7f
	s_mov_b32 s99, 0
	s_mov_b32 s92, 0
	s_branch .LBB0_1239

.LBB0_1239:
	s_add_i32 s6, s92, s29
	s_and_b32 s56, s6, 7
	s_bitcmp1_b32 s99, s56
	s_cbranch_scc1 .LBB0_1238
	s_lshl_b32 s7, s56, 2
	s_add_u32 s68, s24, s7
	s_addc_u32 s69, s25, 0
	s_and_b32 s6, s6, 1
	s_lshl_b32 s7, s6, 3
	s_add_i32 s7, s7, s93
	s_lshl_b32 s57, s7, 7
	s_lshl_b32 s34, s7, 6
	s_mul_i32 s7, s7, 3
	s_addk_i32 s57, 0x800
	s_lshl_b32 s6, s6, 6
	s_lshl_b32 s70, s7, 1
	s_branch .LBB0_1242

.LBB0_1246:
	s_or_b64 exec, exec, s[10:11]
	s_waitcnt vmcnt(0)
	v_readfirstlane_b32 s7, v2
	s_nop 1
	s_cmp_lt_u32 s7, 0x80
	v_mov_b32_e32 v12, 0
	s_cbranch_scc1 .Lqm_ok_mixb
	global_load_dwordx4 v[4:7], v1, s[24:25] offset:128 sc1
	global_load_dwordx4 v[8:11], v1, s[24:25] offset:144 sc1
	s_waitcnt vmcnt(0)
	v_lshrrev_b32_e32 v13, 7, v4
	v_min_u32_e32 v13, 1, v13
	v_lshl_or_b32 v12, v13, 16, v12
	v_lshrrev_b32_e32 v13, 7, v5
	v_min_u32_e32 v13, 1, v13
	v_lshl_or_b32 v12, v13, 17, v12
	v_lshrrev_b32_e32 v13, 7, v6
	v_min_u32_e32 v13, 1, v13
	v_lshl_or_b32 v12, v13, 18, v12
	v_lshrrev_b32_e32 v13, 7, v7
	v_min_u32_e32 v13, 1, v13
	v_lshl_or_b32 v12, v13, 19, v12
	v_lshrrev_b32_e32 v13, 7, v8
	v_min_u32_e32 v13, 1, v13
	v_lshl_or_b32 v12, v13, 20, v12
	v_lshrrev_b32_e32 v13, 7, v9
	v_min_u32_e32 v13, 1, v13
	v_lshl_or_b32 v12, v13, 21, v12
	v_lshrrev_b32_e32 v13, 7, v10
	v_min_u32_e32 v13, 1, v13
	v_lshl_or_b32 v12, v13, 22, v12
	v_lshrrev_b32_e32 v13, 7, v11
	v_min_u32_e32 v13, 1, v13
	v_lshl_or_b32 v12, v13, 23, v12
.Lqm_ok_mixb:
	v_mov_b32_e32 v2, s81
	s_nop 0
	v_add_u32_e32 v0, s7, v0
	v_or_b32_e32 v0, v0, v12
	ds_write_b32 v2, v0

.LBB0_1248:
	s_waitcnt lgkmcnt(0)
	s_barrier
	ds_read_b32 v0, v190
	s_mov_b64 s[8:9], -1
	s_waitcnt lgkmcnt(0)
	s_nop 0
	v_readfirstlane_b32 s98, v0
	v_and_b32_e32 v0, 0xffff, v0
	s_nop 1
	s_lshr_b32 s98, s98, 16
	s_or_b32 s99, s99, s98
	v_cmp_lt_i32_e32 vcc, s82, v0
	v_readfirstlane_b32 s7, v0
	s_cbranch_vccnz .LBB0_1241
	v_mbcnt_lo_u32_b32 v84, -1, 0
	v_mbcnt_hi_u32_b32 v84, -1, v84
	s_movk_i32 s8, 0x1020
	v_add_u32_e32 v2, s57, v84
	v_ashrrev_i32_e32 v3, 31, v2
	v_lshl_add_u64 v[2:3], v[2:3], 2, s[64:65]
	global_load_dword v0, v[2:3], off
	s_nop 0
	global_load_dword v2, v[2:3], off offset:256
	v_add_u32_e32 v87, s91, v84
	v_lshl_add_u32 v3, v84, 2, s3
	v_cmp_gt_i32_e32 vcc, s8, v87
	s_waitcnt vmcnt(0)
	ds_write2st64_b32 v3, v0, v2 offset1:1
	s_and_saveexec_b64 s[8:9], vcc
	s_cbranch_execz .LBB0_1252
	v_add_u32_e32 v0, s30, v84
	v_lshl_add_u32 v2, v84, 2, s35
	s_mov_b64 s[10:11], 0

.LBB0_2614:
	s_add_i32 s13, 0, 0x21200
	s_mov_b32 s7, 0
	s_getreg_b32 s12, hwreg(HW_REG_XCC_ID, 0, 4)
	v_mov_b32_e32 v1, 0
	v_mov_b32_e32 v192, s13
	s_movk_i32 s29, 0x7f
	s_movk_i32 s30, 0x1800
	s_mov_b32 s34, 0x40000
	s_movk_i32 s35, 0x190
	s_movk_i32 s44, 0xffb0
	s_movk_i32 s45, 0x3200
	s_movk_i32 s46, 0x140
	s_movk_i32 s48, 0x80
	v_mov_b32_e32 v193, 0xf149f2ca
	s_mov_b32 s99, 0
	s_mov_b32 s49, 0
	s_branch .LBB0_2616

.LBB0_2616:
	s_add_i32 s6, s49, s12
	s_and_b32 s56, s6, 7
	s_bitcmp1_b32 s99, s56
	s_cbranch_scc1 .LBB0_2615
	s_lshl_b32 s6, s56, 2
	s_add_u32 s14, s24, s6
	s_addc_u32 s15, s25, 0
	s_branch .LBB0_2620

.LBB0_2624:
	s_or_b64 exec, exec, s[22:23]
	s_waitcnt vmcnt(0)
	v_readfirstlane_b32 s6, v2
	s_nop 1
	s_cmp_lt_u32 s6, 0x80
	v_mov_b32_e32 v240, 0
	s_cbranch_scc1 .Lqm_ok_mla
	global_load_dwordx4 v[232:235], v1, s[24:25] offset:192 sc1
	global_load_dwordx4 v[236:239], v1, s[24:25] offset:208 sc1
	s_waitcnt vmcnt(0)
	v_lshrrev_b32_e32 v241, 7, v232
	v_min_u32_e32 v241, 1, v241
	v_lshl_or_b32 v240, v241, 16, v240
	v_lshrrev_b32_e32 v241, 7, v233
	v_min_u32_e32 v241, 1, v241
	v_lshl_or_b32 v240, v241, 17, v240
	v_lshrrev_b32_e32 v241, 7, v234
	v_min_u32_e32 v241, 1, v241
	v_lshl_or_b32 v240, v241, 18, v240
	v_lshrrev_b32_e32 v241, 7, v235
	v_min_u32_e32 v241, 1, v241
	v_lshl_or_b32 v240, v241, 19, v240
	v_lshrrev_b32_e32 v241, 7, v236
	v_min_u32_e32 v241, 1, v241
	v_lshl_or_b32 v240, v241, 20, v240
	v_lshrrev_b32_e32 v241, 7, v237
	v_min_u32_e32 v241, 1, v241
	v_lshl_or_b32 v240, v241, 21, v240
	v_lshrrev_b32_e32 v241, 7, v238
	v_min_u32_e32 v241, 1, v241
	v_lshl_or_b32 v240, v241, 22, v240
	v_lshrrev_b32_e32 v241, 7, v239
	v_min_u32_e32 v241, 1, v241
	v_lshl_or_b32 v240, v241, 23, v240
.Lqm_ok_mla:
	v_mov_b32_e32 v2, s13
	s_nop 0
	v_add_u32_e32 v0, s6, v0
	v_or_b32_e32 v0, v0, v240
	ds_write_b32 v2, v0

.LBB0_2626:
	s_waitcnt lgkmcnt(0)
	s_barrier
	ds_read_b32 v0, v192
	s_mov_b64 s[16:17], -1
	s_waitcnt lgkmcnt(0)
	s_nop 0
	v_readfirstlane_b32 s98, v0
	v_and_b32_e32 v0, 0xffff, v0
	s_nop 1
	s_lshr_b32 s98, s98, 16
	s_or_b32 s99, s99, s98
	v_cmp_lt_i32_e32 vcc, s29, v0
	v_readfirstlane_b32 s6, v0
	s_cbranch_vccnz .LBB0_2619
	s_lshl_b32 s17, s6, 5
	s_and_b32 s17, s17, 0x380
	s_lshl_b32 s8, s6, 3
	s_and_b32 s16, s6, 0x60
	s_or_b32 s6, s17, s6
	s_ashr_i32 s57, s6, 7
	s_sub_i32 s43, 7, s57
	s_lshl_b32 s23, s43, 8
	s_and_b32 s9, s8, 16
	v_mbcnt_lo_u32_b32 v6, -1, 0
	v_mbcnt_hi_u32_b32 v6, -1, v6
	s_add_i32 s23, s23, s47
	v_and_b32_e32 v4, 31, v6
	s_or_b32 s9, s9, s16
	s_and_b32 s6, s8, 8
	v_or_b32_e32 v185, s23, v4
	s_or_b32 s22, s6, s56
	v_ashrrev_i32_e32 v5, 5, v6
	v_lshl_add_u32 v184, s9, 7, v185
	v_mov_b64_e32 v[2:3], s[18:19]
	v_mad_i64_i32 v[2:3], s[16:17], v184, s30, v[2:3]
	s_mul_i32 s6, s22, 0x180
	v_lshlrev_b32_e32 v8, 3, v5
	v_lshl_add_u64 v[2:3], v[2:3], 0, s[6:7]
	v_ashrrev_i32_e32 v9, 31, v8
	v_lshl_add_u64 v[8:9], v[8:9], 1, v[2:3]
	global_load_dwordx4 v[112:115], v[8:9], off
	global_load_dwordx4 v[116:119], v[8:9], off offset:32
	global_load_dwordx4 v[120:123], v[8:9], off offset:64
	global_load_dwordx4 v[124:127], v[8:9], off offset:96
	global_load_dwordx4 v[128:131], v[8:9], off offset:128
	global_load_dwordx4 v[132:135], v[8:9], off offset:160
	global_load_dwordx4 v[136:139], v[8:9], off offset:192
	global_load_dwordx4 v[140:143], v[8:9], off offset:224
	s_lshl_b32 s6, s9, 20
	s_add_u32 s6, s20, s6
	v_add_u32_e32 v0, s91, v6
	s_addc_u32 s8, s21, 0
	s_lshl_b32 s16, s22, 9
	v_lshlrev_b32_e32 v2, 4, v6
	s_add_u32 s60, s6, s16
	v_ashrrev_i32_e32 v7, 4, v0
	v_and_b32_e32 v187, 0xf0, v2
	s_addc_u32 s61, s8, 0
	v_ashrrev_i32_e32 v3, 3, v0
	v_lshl_or_b32 v0, v7, 13, v187
	global_load_dwordx4 v[160:163], v0, s[60:61]
	v_lshl_add_u64 v[188:189], s[60:61], 0, v[0:1]
	s_lshl_b32 s6, s9, 14
	v_add_co_u32_e32 v10, vcc, s34, v188
	s_add_u32 s16, s62, s6
	v_and_b32_e32 v194, 0x70, v2
	v_addc_co_u32_e32 v11, vcc, 0, v189, vcc
	s_addc_u32 s17, s63, 0
	v_lshl_or_b32 v2, v3, 7, v194
	global_load_dwordx4 v[168:171], v[10:11], off
	global_load_dwordx4 v[164:167], v2, s[16:17]
	global_load_dwordx4 v[172:175], v0, s[60:61] offset:256
	global_load_dwordx4 v[176:179], v[10:11], off offset:256
	global_load_dwordx4 v[144:147], v[8:9], off offset:256
	global_load_dwordx4 v[148:151], v[8:9], off offset:288
	global_load_dwordx4 v[152:155], v[8:9], off offset:320
	global_load_dwordx4 v[156:159], v[8:9], off offset:352
	v_mul_lo_u32 v195, v7, s35
	v_lshlrev_b32_e32 v186, 2, v5
	v_mul_lo_u32 v196, v3, s35
	v_mul_lo_u32 v0, v7, s44
	v_add3_u32 v3, 0, v195, v187
	s_cmp_gt_i32 s57, 7
	v_add3_u32 v8, 0, v196, v194
	v_add_u32_e32 v9, v3, v0
	v_add3_u32 v0, v3, s45, v0
	s_waitcnt vmcnt(8)
	ds_write_b128 v3, v[160:163]
	s_waitcnt vmcnt(7)
	ds_write_b128 v3, v[168:171] offset:12800
	s_waitcnt vmcnt(6)
	ds_write_b128 v8, v[164:167] offset:256
	s_waitcnt vmcnt(5)
	ds_write_b128 v9, v[172:175] offset:25600
	s_waitcnt vmcnt(4)
	ds_write_b128 v0, v[176:179] offset:23040
	s_waitcnt lgkmcnt(0)
	s_barrier
	s_cbranch_scc1 .LBB0_2617
	v_mov_b32_e32 v3, v1
	v_lshrrev_b32_e32 v0, 2, v6
	v_lshl_add_u64 v[190:191], s[16:17], 0, v[2:3]
	v_and_or_b32 v0, v0, 3, v186
	v_lshlrev_b32_e32 v2, 1, v6
	v_lshlrev_b32_e32 v3, 3, v6
	v_and_b32_e32 v197, 32, v2
	v_mul_lo_u32 v198, v0, s46
	s_lshl_b32 s6, s43, 2
	v_lshlrev_b32_e32 v0, 7, v5
	v_lshlrev_b32_e32 v2, 2, v4
	v_mov_b32_e32 v14, v1
	v_mov_b32_e32 v15, v1
	v_and_b32_e32 v199, 24, v3
	v_mul_lo_u32 v201, v7, s46
	v_mul_u32_u24_e32 v203, 0x190, v4
	v_lshlrev_b32_e32 v204, 4, v5
	v_bitop3_b32 v205, v0, s48, v2 bitop3:0x36
	s_or_b32 s43, s6, 3
	s_lshl_b32 s6, s57, 2
	v_mov_b32_e32 v0, v1
	v_mov_b32_e32 v2, v1
	v_mov_b32_e32 v3, v1
	v_mov_b32_e32 v4, v1
	v_mov_b32_e32 v5, v1
	v_mov_b32_e32 v6, v1
	v_mov_b32_e32 v7, v1
	v_mov_b32_e32 v8, v1
	v_mov_b32_e32 v9, v1
	v_mov_b32_e32 v10, v1
	v_mov_b32_e32 v11, v1
	v_mov_b32_e32 v12, v1
	v_mov_b32_e32 v13, v1
	v_mov_b64_e32 v[30:31], v[14:15]
	v_mov_b64_e32 v[46:47], v[14:15]
	v_mov_b64_e32 v[62:63], v[14:15]
	v_mov_b64_e32 v[78:79], v[14:15]
	v_add_u32_e32 v200, 0x3200, v195
	v_add_u32_e32 v202, 0x2800, v201
	s_or_b32 s42, s23, 31
	s_sub_i32 s57, 32, s6
	s_mov_b32 s64, 0
	v_mov_b32_e32 v206, 0
	v_mov_b32_e32 v207, 0xf149f2ca
	v_mov_b64_e32 v[28:29], v[12:13]
	v_mov_b64_e32 v[26:27], v[10:11]
	v_mov_b64_e32 v[24:25], v[8:9]
	v_mov_b64_e32 v[22:23], v[6:7]
	v_mov_b64_e32 v[20:21], v[4:5]
	v_mov_b64_e32 v[18:19], v[2:3]
	v_mov_b64_e32 v[16:17], v[0:1]
	v_mov_b64_e32 v[44:45], v[12:13]
	v_mov_b64_e32 v[42:43], v[10:11]
	v_mov_b64_e32 v[40:41], v[8:9]
	v_mov_b64_e32 v[38:39], v[6:7]
	v_mov_b64_e32 v[36:37], v[4:5]
	v_mov_b64_e32 v[34:35], v[2:3]
	v_mov_b64_e32 v[32:33], v[0:1]
	v_mov_b64_e32 v[60:61], v[12:13]
	v_mov_b64_e32 v[58:59], v[10:11]
	v_mov_b64_e32 v[56:57], v[8:9]
	v_mov_b64_e32 v[54:55], v[6:7]
	v_mov_b64_e32 v[52:53], v[4:5]
	v_mov_b64_e32 v[50:51], v[2:3]
	v_mov_b64_e32 v[48:49], v[0:1]
	v_mov_b64_e32 v[76:77], v[12:13]
	v_mov_b64_e32 v[74:75], v[10:11]
	v_mov_b64_e32 v[72:73], v[8:9]
	v_mov_b64_e32 v[70:71], v[6:7]
	v_mov_b64_e32 v[68:69], v[4:5]
	v_mov_b64_e32 v[66:67], v[2:3]
	v_mov_b64_e32 v[64:65], v[0:1]
	s_mov_b32 s65, 0
	s_cmp_lt_i32 s65, s43
	s_cselect_b64 s[16:17], -1, 0
	s_cmp_ge_i32 s65, s43
	s_cbranch_scc1 .LBB0_2630
